# P7 residual row loop: post-norm gains loaded once per layer, next row prefetched into spare registers before the current row is processed, gain-load/store-drain waits removed
# speedup vs baseline: 1.0136x; 1.0076x over previous
.LBB0_941:
	s_or_b64 exec, exec, s[0:1]
	v_readlane_b32 s0, v229, 12
	v_readlane_b32 s1, v229, 13
	s_andn2_b64 vcc, exec, s[0:1]
	s_waitcnt lgkmcnt(0)
	s_barrier
	s_cbranch_vccnz .LBB0_964
	v_readlane_b32 s0, v229, 47
	v_readlane_b32 s1, v229, 48
	s_lshl_b32 s22, s0, 11
	s_mov_b32 s2, s0
	s_lshl_b64 s[0:1], s[22:23], 2
	s_add_u32 s4, s42, s0
	s_addc_u32 s5, s43, s1
	s_cmp_lg_u32 s2, 3
	s_cselect_b64 s[6:7], -1, 0
	v_readlane_b32 s2, v229, 23
	v_readlane_b32 s8, v230, 0
	v_and_b32_e32 v170, 63, v194
	v_lshlrev_b32_e32 v170, 5, v170
	v_add_u32_e32 v171, 0x1000, v170
	global_load_dwordx4 v[136:139], v170, s[4:5]
	global_load_dwordx4 v[140:143], v170, s[4:5] offset:16
	global_load_dwordx4 v[144:147], v170, s[4:5] offset:2048
	global_load_dwordx4 v[148:151], v170, s[4:5] offset:2064
	global_load_dwordx4 v[152:155], v171, s[4:5]
	global_load_dwordx4 v[156:159], v171, s[4:5] offset:16
	global_load_dwordx4 v[160:163], v171, s[4:5] offset:2048
	global_load_dwordx4 v[164:167], v171, s[4:5] offset:2064
	s_mov_b32 s32, 1
	s_lshl_b32 s100, s40, 12
	s_mov_b32 s101, 0
	s_branch .LBB0_945

.LBB0_945:
	v_mov_b32_e32 v1, v194
	v_mov_b32_e32 v7, v0
	v_ashrrev_i32_e32 v1, 6, v1
	v_add_u32_e32 v22, s2, v1
	v_mov_b32_e32 v1, v194
	v_ashrrev_i32_e32 v23, 31, v22
	v_and_b32_e32 v1, 63, v1
	s_waitcnt lgkmcnt(0)
	v_lshlrev_b64 v[2:3], 12, v[22:23]
	v_lshl_add_u64 v[4:5], s[98:99], 0, v[2:3]
	v_lshlrev_b32_e32 v6, 4, v1
	v_lshl_add_u64 v[4:5], v[4:5], 0, v[6:7]
	v_mov_b32_e32 v168, v4
	v_mov_b32_e32 v169, v5
	v_and_b32_e32 v4, 64, v203
	v_readlane_b32 s0, v230, 1
	v_xor_b32_e32 v5, 32, v203
	v_add_u32_e32 v100, 64, v4
	v_lshlrev_b32_e32 v54, 5, v1
	v_readlane_b32 s1, v230, 2
	v_cmp_lt_i32_e32 vcc, v5, v100
	v_lshl_add_u64 v[2:3], s[0:1], 0, v[2:3]
	v_cndmask_b32_e32 v4, v203, v5, vcc
	v_lshl_add_u64 v[24:25], v[2:3], 0, v[6:7]
	v_lshlrev_b32_e32 v58, 2, v4
	s_cmp_eq_u32 s32, 0
	s_cbranch_scc1 .Lp7_have
	global_load_dwordx4 v[104:107], v[168:169], off
	global_load_dwordx4 v[108:111], v[168:169], off offset:1024
	global_load_dwordx4 v[112:115], v[168:169], off offset:2048
	global_load_dwordx4 v[116:119], v[168:169], off offset:3072
	global_load_dwordx4 v[120:123], v[24:25], off
	global_load_dwordx4 v[124:127], v[24:25], off offset:1024
	global_load_dwordx4 v[128:131], v[24:25], off offset:2048
	global_load_dwordx4 v[132:135], v[24:25], off offset:3072
	s_mov_b32 s32, 0
	s_waitcnt vmcnt(0)
	s_branch .Lp7_mov
.Lp7_have:
	s_waitcnt vmcnt(4)
.Lp7_mov:
	v_mov_b32_e32 v14, v104
	v_mov_b32_e32 v15, v105
	v_mov_b32_e32 v16, v106
	v_mov_b32_e32 v17, v107
	v_mov_b32_e32 v18, v108
	v_mov_b32_e32 v19, v109
	v_mov_b32_e32 v20, v110
	v_mov_b32_e32 v21, v111
	v_mov_b32_e32 v26, v112
	v_mov_b32_e32 v27, v113
	v_mov_b32_e32 v28, v114
	v_mov_b32_e32 v29, v115
	v_mov_b32_e32 v42, v116
	v_mov_b32_e32 v43, v117
	v_mov_b32_e32 v44, v118
	v_mov_b32_e32 v45, v119
	v_mov_b32_e32 v72, v120
	v_mov_b32_e32 v73, v121
	v_mov_b32_e32 v74, v122
	v_mov_b32_e32 v75, v123
	v_mov_b32_e32 v10, v124
	v_mov_b32_e32 v11, v125
	v_mov_b32_e32 v12, v126
	v_mov_b32_e32 v13, v127
	v_mov_b32_e32 v6, v128
	v_mov_b32_e32 v7, v129
	v_mov_b32_e32 v8, v130
	v_mov_b32_e32 v9, v131
	v_mov_b32_e32 v2, v132
	v_mov_b32_e32 v3, v133
	v_mov_b32_e32 v4, v134
	v_mov_b32_e32 v5, v135
	s_add_i32 vcc_lo, s8, s34
	s_cmpk_gt_i32 vcc_lo, 0x7ff
	s_cbranch_scc1 .Lp7_nopf
	v_lshl_add_u64 v[168:169], v[168:169], 0, s[100:101]
	v_lshl_add_u64 v[170:171], v[24:25], 0, s[100:101]
	global_load_dwordx4 v[104:107], v[168:169], off
	global_load_dwordx4 v[108:111], v[168:169], off offset:1024
	global_load_dwordx4 v[112:115], v[168:169], off offset:2048
	global_load_dwordx4 v[116:119], v[168:169], off offset:3072
	global_load_dwordx4 v[120:123], v[170:171], off
	global_load_dwordx4 v[124:127], v[170:171], off offset:1024
	global_load_dwordx4 v[128:131], v[170:171], off offset:2048
	global_load_dwordx4 v[132:135], v[170:171], off offset:3072
.Lp7_nopf:
	v_xor_b32_e32 v55, 16, v203
	v_cmp_lt_i32_e32 vcc, v55, v100
	v_xor_b32_e32 v98, 8, v203
	v_xor_b32_e32 v99, 4, v203
	s_mov_b64 s[50:51], -1
	v_lshlrev_b32_e32 v56, 16, v14
	v_and_b32_e32 v57, 0xffff0000, v14
	v_lshlrev_b32_e32 v14, 16, v15
	v_and_b32_e32 v15, 0xffff0000, v15
	v_pk_mul_f32 v[96:97], v[56:57], v[56:57]
	v_pk_mul_f32 v[94:95], v[14:15], v[14:15]
	v_add_f32_e32 v59, v96, v97
	v_lshlrev_b32_e32 v76, 16, v16
	v_and_b32_e32 v77, 0xffff0000, v16
	v_add_f32_e32 v59, v59, v94
	v_pk_mul_f32 v[92:93], v[76:77], v[76:77]
	v_add_f32_e32 v59, v95, v59
	v_lshlrev_b32_e32 v16, 16, v17
	v_and_b32_e32 v17, 0xffff0000, v17
	v_add_f32_e32 v59, v92, v59
	v_pk_mul_f32 v[90:91], v[16:17], v[16:17]
	v_add_f32_e32 v59, v93, v59
	v_lshlrev_b32_e32 v48, 16, v18
	v_and_b32_e32 v49, 0xffff0000, v18
	v_add_f32_e32 v59, v90, v59
	v_lshlrev_b32_e32 v46, 16, v19
	v_and_b32_e32 v47, 0xffff0000, v19
	v_pk_mul_f32 v[18:19], v[48:49], v[48:49]
	v_add_f32_e32 v59, v91, v59
	v_add_f32_e32 v18, v59, v18
	v_lshlrev_b32_e32 v52, 16, v20
	v_and_b32_e32 v53, 0xffff0000, v20
	v_lshlrev_b32_e32 v50, 16, v21
	v_and_b32_e32 v51, 0xffff0000, v21
	v_pk_mul_f32 v[20:21], v[46:47], v[46:47]
	v_add_f32_e32 v18, v19, v18
	v_add_f32_e32 v18, v20, v18
	v_lshlrev_b32_e32 v36, 16, v26
	v_and_b32_e32 v37, 0xffff0000, v26
	v_lshlrev_b32_e32 v34, 16, v27
	v_and_b32_e32 v35, 0xffff0000, v27
	v_lshlrev_b32_e32 v40, 16, v28
	v_and_b32_e32 v41, 0xffff0000, v28
	v_lshlrev_b32_e32 v38, 16, v29
	v_and_b32_e32 v39, 0xffff0000, v29
	v_lshlrev_b32_e32 v28, 16, v42
	v_and_b32_e32 v29, 0xffff0000, v42
	v_lshlrev_b32_e32 v26, 16, v43
	v_and_b32_e32 v27, 0xffff0000, v43
	v_pk_mul_f32 v[42:43], v[52:53], v[52:53]
	v_add_f32_e32 v18, v21, v18
	v_add_f32_e32 v18, v42, v18
	v_lshlrev_b32_e32 v32, 16, v44
	v_and_b32_e32 v33, 0xffff0000, v44
	v_lshlrev_b32_e32 v30, 16, v45
	v_and_b32_e32 v31, 0xffff0000, v45
	v_pk_mul_f32 v[44:45], v[50:51], v[50:51]
	v_add_f32_e32 v18, v43, v18
	v_add_f32_e32 v18, v44, v18
	v_pk_mul_f32 v[60:61], v[36:37], v[36:37]
	v_add_f32_e32 v18, v45, v18
	v_add_f32_e32 v18, v18, v60
	v_pk_mul_f32 v[62:63], v[34:35], v[34:35]
	v_add_f32_e32 v18, v61, v18
	v_add_f32_e32 v18, v62, v18
	v_pk_mul_f32 v[78:79], v[40:41], v[40:41]
	v_add_f32_e32 v18, v63, v18
	v_add_f32_e32 v18, v78, v18
	v_pk_mul_f32 v[80:81], v[38:39], v[38:39]
	v_add_f32_e32 v18, v79, v18
	v_add_f32_e32 v18, v80, v18
	v_pk_mul_f32 v[82:83], v[28:29], v[28:29]
	v_add_f32_e32 v18, v81, v18
	v_add_f32_e32 v18, v18, v82
	v_pk_mul_f32 v[84:85], v[26:27], v[26:27]
	v_add_f32_e32 v18, v83, v18
	v_add_f32_e32 v18, v84, v18
	v_pk_mul_f32 v[86:87], v[32:33], v[32:33]
	v_add_f32_e32 v18, v85, v18
	v_add_f32_e32 v18, v86, v18
	v_pk_mul_f32 v[88:89], v[30:31], v[30:31]
	v_add_f32_e32 v18, v87, v18
	v_add_f32_e32 v18, v88, v18
	v_add_f32_e32 v18, v89, v18
	ds_bpermute_b32 v19, v58, v18
	v_cndmask_b32_e32 v21, v203, v55, vcc
	v_lshlrev_b32_e32 v59, 2, v21
	v_cmp_lt_i32_e32 vcc, v98, v100
	v_xor_b32_e32 v20, 2, v203
	s_waitcnt lgkmcnt(0)
	v_add_f32_e32 v18, v18, v19
	ds_bpermute_b32 v19, v59, v18
	v_cndmask_b32_e32 v42, v203, v98, vcc
	v_lshlrev_b32_e32 v60, 2, v42
	v_cmp_lt_i32_e32 vcc, v99, v100
	v_xor_b32_e32 v21, 1, v203
	s_waitcnt lgkmcnt(0)
	v_add_f32_e32 v18, v18, v19
	ds_bpermute_b32 v19, v60, v18
	v_cndmask_b32_e32 v43, v203, v99, vcc
	v_lshlrev_b32_e32 v61, 2, v43
	v_cmp_lt_i32_e32 vcc, v20, v100
	v_cndmask_b32_e64 v42, 0, 1, s[6:7]
	s_waitcnt lgkmcnt(0)
	v_add_f32_e32 v18, v18, v19
	ds_bpermute_b32 v19, v61, v18
	v_cndmask_b32_e32 v20, v203, v20, vcc
	v_lshlrev_b32_e32 v62, 2, v20
	v_cmp_lt_i32_e32 vcc, v21, v100
	v_cmp_ne_u32_e64 s[0:1], 1, v42
	s_waitcnt lgkmcnt(0)
	v_add_f32_e32 v19, v18, v19
	ds_bpermute_b32 v20, v62, v19
	v_cndmask_b32_e32 v18, v203, v21, vcc
	v_lshlrev_b32_e32 v63, 2, v18
	v_lshlrev_b32_e32 v18, 16, v72
	v_and_b32_e32 v21, 0xffff0000, v73
	s_waitcnt lgkmcnt(0)
	v_add_f32_e32 v42, v19, v20
	ds_bpermute_b32 v43, v63, v42
	v_and_b32_e32 v19, 0xffff0000, v72
	v_lshlrev_b32_e32 v20, 16, v73
	v_lshlrev_b32_e32 v44, 16, v74
	v_and_b32_e32 v45, 0xffff0000, v74
	s_waitcnt lgkmcnt(0)
	v_add_f32_e32 v42, v42, v43
	v_fmamk_f32 v42, v42, 0x3a000000, v199
	v_mul_f32_e32 v43, 0x4b800000, v42
	v_cmp_gt_f32_e32 vcc, s3, v42
	v_lshlrev_b32_e32 v72, 16, v75
	v_and_b32_e32 v73, 0xffff0000, v75
	v_cndmask_b32_e32 v42, v42, v43, vcc
	v_rsq_f32_e32 v42, v42
	s_nop 0
	v_mul_f32_e32 v43, 0x45800000, v42
	v_cndmask_b32_e32 v42, v42, v43, vcc
	v_pk_mul_f32 v[56:57], v[42:43], v[56:57] op_sel_hi:[0,1]
	v_pk_mul_f32 v[74:75], v[42:43], v[76:77] op_sel_hi:[0,1]
	v_pk_mul_f32 v[76:77], v[42:43], v[14:15] op_sel_hi:[0,1]
	v_pk_mul_f32 v[16:17], v[42:43], v[16:17] op_sel_hi:[0,1]
	v_pk_fma_f32 v[18:19], v[136:137], v[56:57], v[18:19]
	v_pk_fma_f32 v[14:15], v[140:141], v[74:75], v[44:45]
	v_pk_fma_f32 v[20:21], v[138:139], v[76:77], v[20:21]
	v_pk_fma_f32 v[16:17], v[142:143], v[16:17], v[72:73]
	s_andn2_b64 vcc, exec, s[6:7]
	s_cbranch_vccnz .LBB0_947
	v_pk_mul_f32 v[44:45], v[18:19], v[18:19]
	v_pk_mul_f32 v[56:57], v[20:21], v[20:21]
	v_add_f32_e32 v43, v44, v45
	v_add_f32_e32 v43, v56, v43
	v_pk_mul_f32 v[64:65], v[14:15], v[14:15]
	v_add_f32_e32 v43, v57, v43
	v_add_f32_e32 v43, v64, v43
	v_pk_mul_f32 v[66:67], v[16:17], v[16:17]
	v_add_f32_e32 v43, v65, v43
	v_add_f32_e32 v43, v66, v43
	v_add_f32_e32 v65, v67, v43
	v_cvt_pk_bf16_f32 v66, v18, v19
	v_cvt_pk_bf16_f32 v67, v20, v21
	v_cvt_pk_bf16_f32 v68, v14, v15
	v_cvt_pk_bf16_f32 v69, v16, v17
	s_mov_b64 s[50:51], 0
	global_store_dwordx4 v[24:25], v[66:69], off

.LBB0_949:
	v_mov_b32_e32 v55, v0
	v_lshl_add_u64 v[18:19], s[4:5], 0, v[54:55]
	s_nop 0
	v_mov_b32_e32 v43, v42
	v_lshlrev_b32_e32 v54, 16, v10
	v_and_b32_e32 v55, 0xffff0000, v10
	v_lshlrev_b32_e32 v66, 16, v11
	v_and_b32_e32 v67, 0xffff0000, v11
	v_lshlrev_b32_e32 v10, 16, v12
	v_and_b32_e32 v11, 0xffff0000, v12
	v_lshlrev_b32_e32 v12, 16, v13
	v_and_b32_e32 v13, 0xffff0000, v13
	v_pk_mul_f32 v[48:49], v[42:43], v[48:49]
	v_pk_mul_f32 v[52:53], v[42:43], v[52:53]
	v_pk_mul_f32 v[46:47], v[42:43], v[46:47]
	v_pk_mul_f32 v[50:51], v[42:43], v[50:51]
	s_and_b64 vcc, exec, s[0:1]
	s_mov_b64 s[50:51], -1
	v_pk_fma_f32 v[14:15], v[48:49], v[144:145], v[54:55]
	v_pk_fma_f32 v[10:11], v[52:53], v[148:149], v[10:11]
	v_pk_fma_f32 v[16:17], v[46:47], v[146:147], v[66:67]
	v_pk_fma_f32 v[12:13], v[50:51], v[150:151], v[12:13]
	s_cbranch_vccnz .LBB0_951
	v_pk_mul_f32 v[18:19], v[14:15], v[14:15]
	v_cvt_pk_bf16_f32 v46, v14, v15
	v_add_f32_e32 v18, v65, v18
	v_add_f32_e32 v20, v19, v18
	v_pk_mul_f32 v[18:19], v[16:17], v[16:17]
	v_cvt_pk_bf16_f32 v47, v16, v17
	v_add_f32_e32 v18, v18, v20
	v_add_f32_e32 v20, v19, v18
	v_pk_mul_f32 v[18:19], v[10:11], v[10:11]
	v_cvt_pk_bf16_f32 v48, v10, v11
	v_add_f32_e32 v18, v18, v20
	v_add_f32_e32 v20, v19, v18
	v_pk_mul_f32 v[18:19], v[12:13], v[12:13]
	v_cvt_pk_bf16_f32 v49, v12, v13
	v_add_f32_e32 v18, v18, v20
	v_add_f32_e32 v18, v19, v18
	s_mov_b64 s[50:51], 0
	global_store_dwordx4 v[24:25], v[46:49], off offset:1024

.LBB0_953:
	s_nop 0
	v_or_b32_e32 v10, 0x400, v64
	v_lshlrev_b32_e32 v14, 2, v10
	v_lshlrev_b32_e32 v16, 16, v6
	v_and_b32_e32 v17, 0xffff0000, v6
	v_lshlrev_b32_e32 v20, 16, v7
	v_and_b32_e32 v21, 0xffff0000, v7
	v_lshlrev_b32_e32 v6, 16, v8
	v_and_b32_e32 v7, 0xffff0000, v8
	v_lshlrev_b32_e32 v8, 16, v9
	v_and_b32_e32 v9, 0xffff0000, v9
	v_pk_mul_f32 v[36:37], v[42:43], v[36:37]
	v_pk_mul_f32 v[40:41], v[42:43], v[40:41]
	v_pk_mul_f32 v[34:35], v[42:43], v[34:35]
	v_pk_mul_f32 v[38:39], v[42:43], v[38:39]
	s_and_b64 vcc, exec, s[0:1]
	s_mov_b64 s[50:51], -1
	v_pk_fma_f32 v[10:11], v[36:37], v[152:153], v[16:17]
	v_pk_fma_f32 v[6:7], v[40:41], v[156:157], v[6:7]
	v_pk_fma_f32 v[12:13], v[34:35], v[154:155], v[20:21]
	v_pk_fma_f32 v[8:9], v[38:39], v[158:159], v[8:9]
	s_cbranch_vccnz .LBB0_955
	v_pk_mul_f32 v[16:17], v[10:11], v[10:11]
	v_cvt_pk_bf16_f32 v34, v10, v11
	v_add_f32_e32 v15, v18, v16
	v_add_f32_e32 v15, v17, v15
	v_pk_mul_f32 v[16:17], v[12:13], v[12:13]
	v_cvt_pk_bf16_f32 v35, v12, v13
	v_add_f32_e32 v15, v16, v15
	v_add_f32_e32 v15, v17, v15
	v_pk_mul_f32 v[16:17], v[6:7], v[6:7]
	v_cvt_pk_bf16_f32 v36, v6, v7
	v_add_f32_e32 v15, v16, v15
	v_add_f32_e32 v15, v17, v15
	v_pk_mul_f32 v[16:17], v[8:9], v[8:9]
	v_cvt_pk_bf16_f32 v37, v8, v9
	v_add_f32_e32 v15, v16, v15
	v_add_f32_e32 v15, v17, v15
	s_mov_b64 s[50:51], 0
	global_store_dwordx4 v[24:25], v[34:37], off offset:2048

.LBB0_957:
	s_nop 0
	v_or_b32_e32 v6, 0x600, v64
	v_lshlrev_b32_e32 v10, 2, v6
	v_lshlrev_b32_e32 v12, 16, v2
	v_and_b32_e32 v13, 0xffff0000, v2
	v_lshlrev_b32_e32 v20, 16, v3
	v_and_b32_e32 v21, 0xffff0000, v3
	v_lshlrev_b32_e32 v2, 16, v4
	v_and_b32_e32 v3, 0xffff0000, v4
	v_lshlrev_b32_e32 v4, 16, v5
	v_and_b32_e32 v5, 0xffff0000, v5
	v_pk_mul_f32 v[28:29], v[42:43], v[28:29]
	v_pk_mul_f32 v[32:33], v[42:43], v[32:33]
	v_pk_mul_f32 v[26:27], v[42:43], v[26:27]
	v_pk_mul_f32 v[30:31], v[42:43], v[30:31]
	s_and_b64 vcc, exec, s[0:1]
	s_mov_b64 s[50:51], -1
	v_pk_fma_f32 v[6:7], v[28:29], v[160:161], v[12:13]
	v_pk_fma_f32 v[2:3], v[32:33], v[164:165], v[2:3]
	v_pk_fma_f32 v[8:9], v[26:27], v[162:163], v[20:21]
	v_pk_fma_f32 v[4:5], v[30:31], v[166:167], v[4:5]
	s_cbranch_vccnz .LBB0_960
	v_pk_mul_f32 v[12:13], v[6:7], v[6:7]
	v_cvt_pk_bf16_f32 v16, v6, v7
	v_add_f32_e32 v11, v15, v12
	v_add_f32_e32 v11, v13, v11
	v_pk_mul_f32 v[12:13], v[8:9], v[8:9]
	v_cvt_pk_bf16_f32 v17, v8, v9
	v_add_f32_e32 v11, v12, v11
	v_add_f32_e32 v11, v13, v11
	v_pk_mul_f32 v[12:13], v[2:3], v[2:3]
	v_cvt_pk_bf16_f32 v18, v2, v3
	v_add_f32_e32 v11, v12, v11
	v_add_f32_e32 v11, v13, v11
	v_pk_mul_f32 v[12:13], v[4:5], v[4:5]
	v_cvt_pk_bf16_f32 v19, v4, v5
	v_add_f32_e32 v11, v12, v11
	v_add_f32_e32 v11, v13, v11
	global_store_dwordx4 v[24:25], v[16:19], off offset:3072
	s_cbranch_execz .LBB0_961
